# item loop: nothing prefetched past the end of a dealt range (exit test before the V loads, K loads skipped for a range's last item) so a range ends with no load in flight
# speedup vs baseline: 1.0077x; 1.0001x over previous
.Lit_far:
	v_lshlrev_b32_e32 v190, 2, v189
	s_cmp_eq_u32 s24, 0
	s_cbranch_scc1 .Lit_w0
	s_waitcnt vmcnt(8)
	s_branch .Lit_exp

.Lit_noflag:
	s_or_b64 exec, exec, s[16:17]
	s_and_saveexec_b64 s[16:17], s[14:15]
	v_cvt_i32_f32_e32 v3, v18
	v_cvt_i32_f32_e32 v4, v19
	v_cvt_i32_f32_e32 v5, v20
	v_mad_u32_u24 v2, v189, s78, v1
	v_cvt_i32_f32_e32 v6, v21
	ds_add_u32 v2, v3
	ds_add_u32 v2, v4 offset:4
	ds_add_u32 v2, v5 offset:8
	ds_add_u32 v2, v6 offset:12
	v_cvt_i32_f32_e32 v3, v22
	v_cvt_i32_f32_e32 v4, v23
	v_cvt_i32_f32_e32 v5, v24
	v_cvt_i32_f32_e32 v6, v25
	ds_add_u32 v2, v3 offset:32
	ds_add_u32 v2, v4 offset:36
	ds_add_u32 v2, v5 offset:40
	ds_add_u32 v2, v6 offset:44
	v_cvt_i32_f32_e32 v3, v26
	v_cvt_i32_f32_e32 v4, v27
	v_cvt_i32_f32_e32 v5, v28
	v_cvt_i32_f32_e32 v6, v29
	ds_add_u32 v2, v3 offset:64
	ds_add_u32 v2, v4 offset:68
	ds_add_u32 v2, v5 offset:72
	ds_add_u32 v2, v6 offset:76
	v_cvt_i32_f32_e32 v3, v30
	v_cvt_i32_f32_e32 v4, v31
	v_cvt_i32_f32_e32 v5, v32
	v_cvt_i32_f32_e32 v6, v33
	ds_add_u32 v2, v3 offset:96
	ds_add_u32 v2, v4 offset:100
	ds_add_u32 v2, v5 offset:104
	ds_add_u32 v2, v6 offset:108
	v_cvt_i32_f32_e32 v3, v34
	v_cvt_i32_f32_e32 v4, v35
	v_cvt_i32_f32_e32 v5, v36
	v_cvt_i32_f32_e32 v6, v37
	ds_add_u32 v2, v3 offset:128
	ds_add_u32 v2, v4 offset:132
	ds_add_u32 v2, v5 offset:136
	ds_add_u32 v2, v6 offset:140
	v_cvt_i32_f32_e32 v3, v38
	v_cvt_i32_f32_e32 v4, v39
	v_cvt_i32_f32_e32 v5, v40
	v_cvt_i32_f32_e32 v6, v41
	ds_add_u32 v2, v3 offset:160
	ds_add_u32 v2, v4 offset:164
	ds_add_u32 v2, v5 offset:168
	ds_add_u32 v2, v6 offset:172
	v_cvt_i32_f32_e32 v3, v42
	v_cvt_i32_f32_e32 v4, v43
	v_cvt_i32_f32_e32 v5, v44
	v_cvt_i32_f32_e32 v6, v45
	ds_add_u32 v2, v3 offset:192
	ds_add_u32 v2, v4 offset:196
	ds_add_u32 v2, v5 offset:200
	ds_add_u32 v2, v6 offset:204
	v_cvt_i32_f32_e32 v3, v46
	v_cvt_i32_f32_e32 v4, v47
	v_cvt_i32_f32_e32 v5, v48
	v_cvt_i32_f32_e32 v6, v49
	ds_add_u32 v2, v3 offset:224
	ds_add_u32 v2, v4 offset:228
	ds_add_u32 v2, v5 offset:232
	ds_add_u32 v2, v6 offset:236
	s_or_b64 exec, exec, s[16:17]
	s_add_i32 s4, s53, 1
	s_cmp_ge_u32 s4, s32
	s_cbranch_scc1 .Lit_ret
	s_and_b64 vcc, exec, s[12:13]
	s_cbranch_vccnz .Lit_nov
	s_and_b32 s4, s26, 0xff
	s_lshl_b32 s4, s4, 13
	s_add_u32 s4, s50, s4
	s_addc_u32 s5, s51, 0
	global_load_dwordx4 v[74:77], v194, s[4:5]
	global_load_dwordx4 v[70:73], v194, s[4:5] offset:1024
	global_load_dwordx4 v[86:89], v194, s[4:5] offset:2048
	global_load_dwordx4 v[82:85], v194, s[4:5] offset:3072
	global_load_dwordx4 v[94:97], v200, s[4:5]
	global_load_dwordx4 v[102:105], v202, s[4:5]
	global_load_dwordx4 v[106:109], v204, s[4:5]
	global_load_dwordx4 v[110:113], v206, s[4:5]
.Lit_nov:
.Lit_commit:
	s_add_i32 s53, s53, 1
	s_mov_b32 s22, s54
	s_mov_b32 s26, s55
	s_mov_b64 s[12:13], s[56:57]
	s_mov_b64 s[14:15], s[58:59]
	v_mov_b32_e32 v189, v130
	v_mov_b32_e32 v46, v136
	s_cmp_lt_i32 s22, s96
	s_cselect_b64 s[16:17], -1, 0
	s_and_b64 s[60:61], s[8:9], s[14:15]
	s_mov_b32 s24, 0
	s_waitcnt vmcnt(8) lgkmcnt(15)
	v_mfma_f32_32x32x16_bf16 v[18:33], v[50:53], v[114:117], 0
	v_mfma_f32_32x32x16_bf16 v[2:17], v[66:69], v[114:117], 0
	v_mfma_f32_32x32x16_bf16 v[18:33], v[54:57], v[118:121], v[18:33]
	v_mfma_f32_32x32x16_bf16 v[2:17], v[78:81], v[118:121], v[2:17]
	v_mfma_f32_32x32x16_bf16 v[18:33], v[58:61], v[122:125], v[18:33]
	v_mfma_f32_32x32x16_bf16 v[2:17], v[90:93], v[122:125], v[2:17]
	v_mfma_f32_32x32x16_bf16 v[18:33], v[62:65], v[126:129], v[18:33]
	v_mfma_f32_32x32x16_bf16 v[2:17], v[98:101], v[126:129], v[2:17]
	s_and_b64 vcc, exec, s[12:13]
	s_cbranch_vccnz .Lit_top
	s_add_i32 s4, s53, 1
	s_cmp_ge_u32 s4, s32
	s_cbranch_scc1 .Lit_top
	s_mov_b32 s24, 1
	s_and_b32 s4, s26, 0xff
	s_lshl_b32 s4, s4, 13
	s_add_u32 s4, s48, s4
	s_addc_u32 s5, s49, 0
	global_load_dwordx4 v[50:53], v194, s[4:5]
	global_load_dwordx4 v[54:57], v194, s[4:5] offset:1024
	global_load_dwordx4 v[58:61], v194, s[4:5] offset:2048
	global_load_dwordx4 v[62:65], v194, s[4:5] offset:3072
	global_load_dwordx4 v[66:69], v200, s[4:5]
	global_load_dwordx4 v[78:81], v202, s[4:5]
	global_load_dwordx4 v[90:93], v204, s[4:5]
	global_load_dwordx4 v[98:101], v206, s[4:5]
	s_branch .Lit_top
